# P4 epilogue residual x loads software-pipelined 5 row-groups deep (20 loads in flight) instead of one group per round trip
# baseline (speedup 1.0000x reference)
.LBB0_666:
	s_lshl_b32 s10, s6, 8
	s_add_i32 s1, s10, s38
	s_lshl_b32 s0, s7, 5
	v_or_b32_e32 v130, s1, v145
	s_lshl_b32 s1, s8, 8
	s_or_b32 s0, s1, s0
	v_lshrrev_b32_e32 v128, 2, v144
	v_ashrrev_i32_e32 v131, 31, v130
	v_and_or_b32 v128, v128, 12, s0
	v_lshlrev_b64 v[132:133], 13, v[130:131]
	v_ashrrev_i32_e32 v129, 31, v128
	v_lshl_add_u64 v[132:133], s[44:45], 0, v[132:133]
	v_lshl_add_u64 v[148:149], v[128:129], 2, v[132:133]
	s_barrier
	v_mov_b64_e32 v[160:161], v[148:149]
	global_load_dwordx4 v[172:175], v[160:161], off nt
	global_load_dwordx4 v[176:179], v[160:161], off offset:64 nt
	global_load_dwordx4 v[180:183], v[160:161], off offset:512 nt
	global_load_dwordx4 v[184:187], v[160:161], off offset:576 nt
	s_mov_b64 s[12:13], 0x20000
	v_lshl_add_u64 v[164:165], v[160:161], 0, s[12:13]
	global_load_dwordx4 v[188:191], v[164:165], off nt
	global_load_dwordx4 v[192:195], v[164:165], off offset:64 nt
	global_load_dwordx4 v[196:199], v[164:165], off offset:512 nt
	global_load_dwordx4 v[200:203], v[164:165], off offset:576 nt
	s_mov_b64 s[12:13], 0x40000
	v_lshl_add_u64 v[162:163], v[160:161], 0, s[12:13]
	global_load_dwordx4 v[204:207], v[162:163], off nt
	global_load_dwordx4 v[208:211], v[162:163], off offset:64 nt
	global_load_dwordx4 v[212:215], v[162:163], off offset:512 nt
	global_load_dwordx4 v[216:219], v[162:163], off offset:576 nt
	s_mov_b64 s[12:13], 0x60000
	v_lshl_add_u64 v[164:165], v[160:161], 0, s[12:13]
	global_load_dwordx4 v[220:223], v[164:165], off nt
	global_load_dwordx4 v[224:227], v[164:165], off offset:64 nt
	global_load_dwordx4 v[228:231], v[164:165], off offset:512 nt
	global_load_dwordx4 v[232:235], v[164:165], off offset:576 nt
	s_mov_b64 s[12:13], 0x100000
	v_lshl_add_u64 v[162:163], v[160:161], 0, s[12:13]
	global_load_dwordx4 v[240:243], v[162:163], off nt
	global_load_dwordx4 v[244:247], v[162:163], off offset:64 nt
	global_load_dwordx4 v[248:251], v[162:163], off offset:512 nt
	global_load_dwordx4 v[252:255], v[162:163], off offset:576 nt
	v_mbcnt_hi_u32_b32 v148, -1, v169
	v_and_b32_e32 v145, 64, v148
	v_and_b32_e32 v147, 63, v144
	v_xor_b32_e32 v144, 16, v148
	v_add_u32_e32 v154, 64, v145
	v_cmp_lt_i32_e32 vcc, v144, v154
	s_lshl_b32 s2, s7, 2
	s_add_i32 s4, s2, 0
	v_cndmask_b32_e32 v144, v148, v144, vcc
	v_lshlrev_b32_e32 v149, 2, v144
	v_cmp_gt_u32_e64 s[0:1], 16, v147
	s_waitcnt vmcnt(16)
	v_pk_add_f32 v[126:127], v[126:127], v[174:175]
	v_pk_add_f32 v[124:125], v[124:125], v[172:173]
	v_pk_add_f32 v[122:123], v[122:123], v[178:179]
	v_pk_add_f32 v[120:121], v[120:121], v[176:177]
	v_pk_add_f32 v[118:119], v[118:119], v[182:183]
	v_pk_add_f32 v[116:117], v[116:117], v[180:181]
	v_pk_mul_f32 v[132:133], v[126:127], v[126:127]
	v_pk_mul_f32 v[134:135], v[124:125], v[124:125]
	v_pk_mul_f32 v[136:137], v[122:123], v[122:123]
	v_pk_mul_f32 v[138:139], v[120:121], v[120:121]
	v_pk_add_f32 v[114:115], v[114:115], v[186:187]
	v_pk_add_f32 v[112:113], v[112:113], v[184:185]
	s_mov_b64 s[12:13], 0x120000
	v_lshl_add_u64 v[164:165], v[160:161], 0, s[12:13]
	global_load_dwordx4 v[172:175], v[164:165], off nt
	global_load_dwordx4 v[176:179], v[164:165], off offset:64 nt
	global_load_dwordx4 v[180:183], v[164:165], off offset:512 nt
	global_load_dwordx4 v[184:187], v[164:165], off offset:576 nt
	v_pk_mul_f32 v[140:141], v[118:119], v[118:119]
	v_pk_mul_f32 v[142:143], v[116:117], v[116:117]
	v_add_f32_e32 v136, v136, v137
	v_add_f32_e32 v137, v138, v139
	v_add_f32_e32 v132, v132, v133
	v_add_f32_e32 v133, v134, v135
	v_pk_mul_f32 v[144:145], v[114:115], v[114:115]
	v_pk_mul_f32 v[150:151], v[112:113], v[112:113]
	v_add_f32_e32 v134, v140, v141
	v_add_f32_e32 v135, v142, v143
	v_add_f32_e32 v136, v137, v136
	v_add_f32_e32 v132, v133, v132
	v_add_f32_e32 v138, v144, v145
	v_add_f32_e32 v139, v150, v151
	v_add_f32_e32 v133, v135, v134
	v_add_f32_e32 v132, v132, v136
	v_add_f32_e32 v132, v132, v133
	v_add_f32_e32 v133, v139, v138
	v_add_f32_e32 v132, v132, v133
	ds_bpermute_b32 v133, v149, v132
	v_xor_b32_e32 v134, 32, v148
	v_cmp_lt_i32_e32 vcc, v134, v154
	v_lshl_add_u32 v150, v146, 4, s4
	s_waitcnt lgkmcnt(0)
	v_add_f32_e32 v132, v132, v133
	v_cndmask_b32_e32 v134, v148, v134, vcc
	v_lshlrev_b32_e32 v151, 2, v134
	ds_bpermute_b32 v133, v151, v132
	s_and_saveexec_b64 s[2:3], s[0:1]
	s_cbranch_execz .LBB0_668
	s_waitcnt lgkmcnt(0)
	v_add_f32_e32 v132, v132, v133
	ds_write_b32 v150, v132
.LBB0_668:
	s_or_b64 exec, exec, s[2:3]
	v_or_b32_e32 v132, 16, v130
	s_waitcnt lgkmcnt(0)
	v_ashrrev_i32_e32 v133, 31, v132
	v_lshlrev_b64 v[132:133], 13, v[132:133]
	v_lshl_add_u64 v[132:133], s[44:45], 0, v[132:133]
	v_lshl_add_u64 v[144:145], v[128:129], 2, v[132:133]
	s_waitcnt vmcnt(16)
	v_pk_add_f32 v[110:111], v[110:111], v[190:191]
	v_pk_add_f32 v[108:109], v[108:109], v[188:189]
	v_pk_add_f32 v[106:107], v[106:107], v[194:195]
	v_pk_add_f32 v[104:105], v[104:105], v[192:193]
	v_pk_add_f32 v[102:103], v[102:103], v[198:199]
	v_pk_add_f32 v[100:101], v[100:101], v[196:197]
	v_pk_mul_f32 v[132:133], v[110:111], v[110:111]
	v_pk_mul_f32 v[134:135], v[108:109], v[108:109]
	v_pk_mul_f32 v[136:137], v[106:107], v[106:107]
	v_pk_mul_f32 v[138:139], v[104:105], v[104:105]
	v_pk_add_f32 v[98:99], v[98:99], v[202:203]
	v_pk_add_f32 v[96:97], v[96:97], v[200:201]
	s_mov_b64 s[12:13], 0x140000
	v_lshl_add_u64 v[162:163], v[160:161], 0, s[12:13]
	global_load_dwordx4 v[188:191], v[162:163], off nt
	global_load_dwordx4 v[192:195], v[162:163], off offset:64 nt
	global_load_dwordx4 v[196:199], v[162:163], off offset:512 nt
	global_load_dwordx4 v[200:203], v[162:163], off offset:576 nt
	v_pk_mul_f32 v[140:141], v[102:103], v[102:103]
	v_pk_mul_f32 v[142:143], v[100:101], v[100:101]
	v_add_f32_e32 v136, v136, v137
	v_add_f32_e32 v137, v138, v139
	v_add_f32_e32 v132, v132, v133
	v_add_f32_e32 v133, v134, v135
	v_pk_mul_f32 v[144:145], v[98:99], v[98:99]
	v_pk_mul_f32 v[152:153], v[96:97], v[96:97]
	v_add_f32_e32 v134, v140, v141
	v_add_f32_e32 v135, v142, v143
	v_add_f32_e32 v136, v137, v136
	v_add_f32_e32 v132, v133, v132
	v_add_f32_e32 v138, v144, v145
	v_add_f32_e32 v139, v152, v153
	v_add_f32_e32 v133, v135, v134
	v_add_f32_e32 v132, v132, v136
	v_add_f32_e32 v132, v132, v133
	v_add_f32_e32 v133, v139, v138
	v_add_f32_e32 v132, v132, v133
	ds_bpermute_b32 v133, v149, v132
	s_waitcnt lgkmcnt(0)
	v_add_f32_e32 v132, v132, v133
	ds_bpermute_b32 v133, v151, v132
	s_and_saveexec_b64 s[2:3], s[0:1]
	s_cbranch_execz .LBB0_670
	s_waitcnt lgkmcnt(0)
	v_add_f32_e32 v132, v132, v133
	ds_write_b32 v150, v132 offset:256
.LBB0_670:
	s_or_b64 exec, exec, s[2:3]
	v_or_b32_e32 v132, 32, v130
	s_waitcnt lgkmcnt(0)
	v_ashrrev_i32_e32 v133, 31, v132
	v_lshlrev_b64 v[132:133], 13, v[132:133]
	v_lshl_add_u64 v[132:133], s[44:45], 0, v[132:133]
	v_lshl_add_u64 v[144:145], v[128:129], 2, v[132:133]
	s_waitcnt vmcnt(16)
	v_pk_add_f32 v[94:95], v[94:95], v[206:207]
	v_pk_add_f32 v[92:93], v[92:93], v[204:205]
	v_pk_add_f32 v[90:91], v[90:91], v[210:211]
	v_pk_add_f32 v[88:89], v[88:89], v[208:209]
	v_pk_add_f32 v[86:87], v[86:87], v[214:215]
	v_pk_add_f32 v[84:85], v[84:85], v[212:213]
	v_pk_mul_f32 v[132:133], v[94:95], v[94:95]
	v_pk_mul_f32 v[134:135], v[92:93], v[92:93]
	v_pk_mul_f32 v[136:137], v[90:91], v[90:91]
	v_pk_mul_f32 v[138:139], v[88:89], v[88:89]
	v_pk_add_f32 v[82:83], v[82:83], v[218:219]
	v_pk_add_f32 v[80:81], v[80:81], v[216:217]
	s_mov_b64 s[12:13], 0x160000
	v_lshl_add_u64 v[164:165], v[160:161], 0, s[12:13]
	global_load_dwordx4 v[204:207], v[164:165], off nt
	global_load_dwordx4 v[208:211], v[164:165], off offset:64 nt
	global_load_dwordx4 v[212:215], v[164:165], off offset:512 nt
	global_load_dwordx4 v[216:219], v[164:165], off offset:576 nt
	v_pk_mul_f32 v[140:141], v[86:87], v[86:87]
	v_pk_mul_f32 v[142:143], v[84:85], v[84:85]
	v_add_f32_e32 v136, v136, v137
	v_add_f32_e32 v137, v138, v139
	v_add_f32_e32 v132, v132, v133
	v_add_f32_e32 v133, v134, v135
	v_pk_mul_f32 v[144:145], v[82:83], v[82:83]
	v_pk_mul_f32 v[152:153], v[80:81], v[80:81]
	v_add_f32_e32 v134, v140, v141
	v_add_f32_e32 v135, v142, v143
	v_add_f32_e32 v136, v137, v136
	v_add_f32_e32 v132, v133, v132
	v_add_f32_e32 v138, v144, v145
	v_add_f32_e32 v139, v152, v153
	v_add_f32_e32 v133, v135, v134
	v_add_f32_e32 v132, v132, v136
	v_add_f32_e32 v132, v132, v133
	v_add_f32_e32 v133, v139, v138
	v_add_f32_e32 v132, v132, v133
	ds_bpermute_b32 v133, v149, v132
	s_waitcnt lgkmcnt(0)
	v_add_f32_e32 v132, v132, v133
	ds_bpermute_b32 v133, v151, v132
	s_and_saveexec_b64 s[2:3], s[0:1]
	s_cbranch_execz .LBB0_672
	s_waitcnt lgkmcnt(0)
	v_add_f32_e32 v132, v132, v133
	ds_write_b32 v150, v132 offset:512
.LBB0_672:
	s_or_b64 exec, exec, s[2:3]
	v_or_b32_e32 v132, 48, v130
	s_waitcnt lgkmcnt(0)
	v_ashrrev_i32_e32 v133, 31, v132
	v_lshlrev_b64 v[132:133], 13, v[132:133]
	v_lshl_add_u64 v[132:133], s[44:45], 0, v[132:133]
	v_lshl_add_u64 v[144:145], v[128:129], 2, v[132:133]
	s_waitcnt vmcnt(16)
	v_pk_add_f32 v[78:79], v[78:79], v[222:223]
	v_pk_add_f32 v[76:77], v[76:77], v[220:221]
	v_pk_add_f32 v[74:75], v[74:75], v[226:227]
	v_pk_add_f32 v[72:73], v[72:73], v[224:225]
	v_pk_add_f32 v[70:71], v[70:71], v[230:231]
	v_pk_add_f32 v[68:69], v[68:69], v[228:229]
	v_pk_mul_f32 v[132:133], v[78:79], v[78:79]
	v_pk_mul_f32 v[134:135], v[76:77], v[76:77]
	v_pk_mul_f32 v[136:137], v[74:75], v[74:75]
	v_pk_mul_f32 v[138:139], v[72:73], v[72:73]
	v_pk_add_f32 v[66:67], v[66:67], v[234:235]
	v_pk_add_f32 v[64:65], v[64:65], v[232:233]
	v_pk_mul_f32 v[140:141], v[70:71], v[70:71]
	v_pk_mul_f32 v[142:143], v[68:69], v[68:69]
	v_add_f32_e32 v136, v136, v137
	v_add_f32_e32 v137, v138, v139
	v_add_f32_e32 v132, v132, v133
	v_add_f32_e32 v133, v134, v135
	v_pk_mul_f32 v[144:145], v[66:67], v[66:67]
	v_pk_mul_f32 v[152:153], v[64:65], v[64:65]
	v_add_f32_e32 v134, v140, v141
	v_add_f32_e32 v135, v142, v143
	v_add_f32_e32 v136, v137, v136
	v_add_f32_e32 v132, v133, v132
	v_add_f32_e32 v138, v144, v145
	v_add_f32_e32 v139, v152, v153
	v_add_f32_e32 v133, v135, v134
	v_add_f32_e32 v132, v132, v136
	v_add_f32_e32 v132, v132, v133
	v_add_f32_e32 v133, v139, v138
	v_add_f32_e32 v132, v132, v133
	ds_bpermute_b32 v133, v149, v132
	s_waitcnt lgkmcnt(0)
	v_add_f32_e32 v132, v132, v133
	ds_bpermute_b32 v133, v151, v132
	s_and_saveexec_b64 s[2:3], s[0:1]
	s_cbranch_execz .LBB0_674
	s_waitcnt lgkmcnt(0)
	v_add_f32_e32 v132, v132, v133
	ds_write_b32 v150, v132 offset:768
.LBB0_674:
	s_or_b64 exec, exec, s[2:3]
	s_waitcnt lgkmcnt(0)
	v_lshlrev_b64 v[132:133], 13, v[130:131]
	v_lshl_add_u64 v[132:133], s[44:45], 0, v[132:133]
	v_lshl_add_u64 v[132:133], v[128:129], 2, v[132:133]
	s_mov_b64 s[2:3], 0x100000
	v_lshl_add_u64 v[152:153], v[132:133], 0, s[2:3]
	v_add_co_u32_e32 v142, vcc, 0x100000, v132
	v_addc_co_u32_e32 v143, vcc, 0, v133, vcc
	s_nop 0
	v_add_u32_e32 v148, 0x80, v146
	s_waitcnt vmcnt(12)
	v_pk_add_f32 v[58:59], v[58:59], v[246:247]
	v_pk_add_f32 v[56:57], v[56:57], v[244:245]
	v_pk_add_f32 v[54:55], v[54:55], v[250:251]
	v_pk_add_f32 v[62:63], v[62:63], v[242:243]
	v_pk_add_f32 v[60:61], v[60:61], v[240:241]
	v_pk_add_f32 v[52:53], v[52:53], v[248:249]
	v_pk_mul_f32 v[134:135], v[58:59], v[58:59]
	v_pk_mul_f32 v[136:137], v[56:57], v[56:57]
	v_pk_mul_f32 v[138:139], v[54:55], v[54:55]
	v_pk_mul_f32 v[142:143], v[62:63], v[62:63]
	v_pk_mul_f32 v[144:145], v[60:61], v[60:61]
	v_pk_mul_f32 v[140:141], v[52:53], v[52:53]
	v_pk_add_f32 v[50:51], v[50:51], v[254:255]
	v_pk_add_f32 v[48:49], v[48:49], v[252:253]
	v_add_f32_e32 v134, v134, v135
	v_add_f32_e32 v135, v136, v137
	v_add_f32_e32 v136, v138, v139
	v_add_f32_e32 v138, v142, v143
	v_add_f32_e32 v139, v144, v145
	v_pk_mul_f32 v[152:153], v[50:51], v[50:51]
	v_pk_mul_f32 v[154:155], v[48:49], v[48:49]
	v_add_f32_e32 v137, v140, v141
	v_add_f32_e32 v134, v135, v134
	v_add_f32_e32 v138, v139, v138
	v_add_f32_e32 v135, v137, v136
	v_add_f32_e32 v136, v152, v153
	v_add_f32_e32 v137, v154, v155
	v_add_f32_e32 v134, v138, v134
	v_add_f32_e32 v134, v134, v135
	v_add_f32_e32 v135, v137, v136
	v_add_f32_e32 v134, v134, v135
	ds_bpermute_b32 v135, v149, v134
	s_waitcnt lgkmcnt(0)
	v_add_f32_e32 v134, v134, v135
	ds_bpermute_b32 v135, v151, v134
	s_and_saveexec_b64 s[2:3], s[0:1]
	s_cbranch_execz .LBB0_676
	v_lshl_add_u32 v136, v148, 4, s4
	s_waitcnt lgkmcnt(0)
	v_add_f32_e32 v134, v134, v135
	ds_write_b32 v136, v134
.LBB0_676:
	s_or_b64 exec, exec, s[2:3]
	v_add_co_u32_e32 v134, vcc, 0x120000, v132
	s_mov_b64 s[2:3], 0x120000
	s_waitcnt lgkmcnt(0)
	v_addc_co_u32_e32 v135, vcc, 0, v133, vcc
	v_lshl_add_u64 v[132:133], v[132:133], 0, s[2:3]
	s_waitcnt vmcnt(8)
	v_pk_add_f32 v[42:43], v[42:43], v[178:179]
	v_pk_add_f32 v[46:47], v[46:47], v[174:175]
	v_pk_add_f32 v[44:45], v[44:45], v[172:173]
	v_pk_add_f32 v[40:41], v[40:41], v[176:177]
	v_pk_add_f32 v[38:39], v[38:39], v[182:183]
	v_pk_add_f32 v[36:37], v[36:37], v[180:181]
	v_pk_mul_f32 v[132:133], v[46:47], v[46:47]
	v_pk_mul_f32 v[134:135], v[44:45], v[44:45]
	v_pk_mul_f32 v[136:137], v[42:43], v[42:43]
	v_pk_mul_f32 v[138:139], v[40:41], v[40:41]
	v_pk_add_f32 v[34:35], v[34:35], v[186:187]
	v_pk_add_f32 v[32:33], v[32:33], v[184:185]
	v_pk_mul_f32 v[140:141], v[38:39], v[38:39]
	v_pk_mul_f32 v[142:143], v[36:37], v[36:37]
	v_add_f32_e32 v132, v132, v133
	v_add_f32_e32 v133, v134, v135
	v_add_f32_e32 v134, v136, v137
	v_add_f32_e32 v135, v138, v139
	v_pk_mul_f32 v[144:145], v[34:35], v[34:35]
	v_pk_mul_f32 v[152:153], v[32:33], v[32:33]
	v_add_f32_e32 v136, v140, v141
	v_add_f32_e32 v137, v142, v143
	v_add_f32_e32 v132, v133, v132
	v_add_f32_e32 v133, v135, v134
	v_add_f32_e32 v138, v144, v145
	v_add_f32_e32 v139, v152, v153
	v_add_f32_e32 v134, v137, v136
	v_add_f32_e32 v132, v132, v133
	v_add_f32_e32 v132, v132, v134
	v_add_f32_e32 v133, v139, v138
	v_add_f32_e32 v132, v132, v133
	ds_bpermute_b32 v133, v149, v132
	s_waitcnt lgkmcnt(0)
	v_add_f32_e32 v132, v132, v133
	ds_bpermute_b32 v133, v151, v132
	s_and_saveexec_b64 s[2:3], s[0:1]
	s_cbranch_execz .LBB0_678
	s_waitcnt lgkmcnt(0)
	v_add_f32_e32 v132, v132, v133
	ds_write_b32 v150, v132 offset:2304
.LBB0_678:
	s_or_b64 exec, exec, s[2:3]
	v_lshlrev_b64 v[130:131], 13, v[130:131]
	v_lshl_add_u64 v[130:131], s[44:45], 0, v[130:131]
	v_lshl_add_u64 v[130:131], v[128:129], 2, v[130:131]
	s_mov_b64 s[2:3], 0x140000
	v_lshl_add_u64 v[144:145], v[130:131], 0, s[2:3]
	v_add_co_u32_e32 v140, vcc, 0x140000, v130
	s_waitcnt lgkmcnt(0)
	v_addc_co_u32_e32 v141, vcc, 0, v131, vcc
	s_nop 0
	s_waitcnt vmcnt(4)
	v_pk_add_f32 v[26:27], v[26:27], v[194:195]
	v_pk_add_f32 v[24:25], v[24:25], v[192:193]
	v_pk_add_f32 v[22:23], v[22:23], v[198:199]
	v_pk_add_f32 v[30:31], v[30:31], v[190:191]
	v_pk_add_f32 v[28:29], v[28:29], v[188:189]
	v_pk_add_f32 v[20:21], v[20:21], v[196:197]
	v_pk_mul_f32 v[132:133], v[26:27], v[26:27]
	v_pk_mul_f32 v[134:135], v[24:25], v[24:25]
	v_pk_mul_f32 v[136:137], v[22:23], v[22:23]
	v_pk_mul_f32 v[140:141], v[30:31], v[30:31]
	v_pk_mul_f32 v[142:143], v[28:29], v[28:29]
	v_pk_mul_f32 v[138:139], v[20:21], v[20:21]
	v_pk_add_f32 v[18:19], v[18:19], v[202:203]
	v_pk_add_f32 v[16:17], v[16:17], v[200:201]
	v_add_f32_e32 v132, v132, v133
	v_add_f32_e32 v133, v134, v135
	v_add_f32_e32 v134, v136, v137
	v_add_f32_e32 v136, v140, v141
	v_add_f32_e32 v137, v142, v143
	v_pk_mul_f32 v[144:145], v[18:19], v[18:19]
	v_pk_mul_f32 v[152:153], v[16:17], v[16:17]
	v_add_f32_e32 v135, v138, v139
	v_add_f32_e32 v132, v133, v132
	v_add_f32_e32 v136, v137, v136
	v_add_f32_e32 v133, v135, v134
	v_add_f32_e32 v134, v144, v145
	v_add_f32_e32 v135, v152, v153
	v_add_f32_e32 v132, v136, v132
	v_add_f32_e32 v132, v132, v133
	v_add_f32_e32 v133, v135, v134
	v_add_f32_e32 v132, v132, v133
	ds_bpermute_b32 v133, v149, v132
	s_waitcnt lgkmcnt(0)
	v_add_f32_e32 v132, v132, v133
	ds_bpermute_b32 v133, v151, v132
	s_and_saveexec_b64 s[2:3], s[0:1]
	s_cbranch_execz .LBB0_680
	s_waitcnt lgkmcnt(0)
	v_add_f32_e32 v132, v132, v133
	ds_write_b32 v150, v132 offset:2560
.LBB0_680:
	s_or_b64 exec, exec, s[2:3]
	v_add_co_u32_e32 v132, vcc, 0x160000, v130
	s_mov_b64 s[2:3], 0x160000
	s_waitcnt lgkmcnt(0)
	v_addc_co_u32_e32 v133, vcc, 0, v131, vcc
	v_lshl_add_u64 v[130:131], v[130:131], 0, s[2:3]
	s_waitcnt vmcnt(0)
	v_pk_add_f32 v[138:139], v[10:11], v[210:211]
	v_pk_add_f32 v[142:143], v[14:15], v[206:207]
	v_pk_add_f32 v[144:145], v[12:13], v[204:205]
	v_pk_add_f32 v[140:141], v[8:9], v[208:209]
	v_pk_add_f32 v[134:135], v[6:7], v[214:215]
	v_pk_add_f32 v[136:137], v[4:5], v[212:213]
	v_pk_add_f32 v[130:131], v[2:3], v[218:219]
	v_pk_add_f32 v[132:133], v[0:1], v[216:217]
	v_pk_mul_f32 v[0:1], v[142:143], v[142:143]
	v_pk_mul_f32 v[2:3], v[144:145], v[144:145]
	v_pk_mul_f32 v[4:5], v[138:139], v[138:139]
	v_pk_mul_f32 v[6:7], v[140:141], v[140:141]
	v_pk_mul_f32 v[8:9], v[134:135], v[134:135]
	v_pk_mul_f32 v[10:11], v[136:137], v[136:137]
	v_add_f32_e32 v0, v0, v1
	v_add_f32_e32 v1, v2, v3
	v_add_f32_e32 v2, v4, v5
	v_add_f32_e32 v3, v6, v7
	v_pk_mul_f32 v[12:13], v[130:131], v[130:131]
	v_pk_mul_f32 v[14:15], v[132:133], v[132:133]
	v_add_f32_e32 v4, v8, v9
	v_add_f32_e32 v5, v10, v11
	v_add_f32_e32 v0, v1, v0
	v_add_f32_e32 v1, v3, v2
	v_add_f32_e32 v6, v12, v13
	v_add_f32_e32 v7, v14, v15
	v_add_f32_e32 v2, v5, v4
	v_add_f32_e32 v0, v0, v1
	v_add_f32_e32 v0, v0, v2
	v_add_f32_e32 v1, v7, v6
	v_add_f32_e32 v0, v0, v1
	ds_bpermute_b32 v1, v149, v0
	s_waitcnt lgkmcnt(0)
	v_add_f32_e32 v0, v0, v1
	ds_bpermute_b32 v1, v151, v0
	s_and_saveexec_b64 s[2:3], s[0:1]
	s_cbranch_execz .LBB0_682
	s_waitcnt lgkmcnt(0)
	v_add_f32_e32 v0, v0, v1
	ds_write_b32 v150, v0 offset:2816
